# up2 chunk-gating item: weight fragments, u values and biases loaded up front (one round trip instead of 24 serialized load-wait-use rounds)
# speedup vs baseline: 1.0066x; 1.0059x over previous
.LBB0_485:
	s_or_b64 exec, exec, s[8:9]
	v_add_u32_e32 v0, s15, v58
	v_ashrrev_i32_e32 v1, 31, v0
	s_and_b32 s8, s1, 3
	v_lshlrev_b64 v[0:1], 10, v[0:1]
	v_lshl_add_u64 v[0:1], v[48:49], 0, v[0:1]
	s_lshl_b32 s54, s8, 7
	v_lshl_add_u64 v[4:5], v[0:1], 0, s[54:55]
	s_waitcnt lgkmcnt(0)
	s_barrier
	global_load_dwordx4 v[0:3], v[4:5], off offset:512
	s_nop 0
	global_load_dwordx4 v[4:7], v[4:5], off offset:528
	s_mov_b32 s7, s55
	s_lshl_b32 s6, s8, 8
	v_lshl_add_u64 v[32:33], v[36:37], 0, s[6:7]
	v_lshl_add_u64 v[50:51], v[38:39], 0, s[6:7]
	global_load_dwordx4 v[8:11], v[50:51], off
	global_load_dwordx4 v[12:15], v[32:33], off
	global_load_dwordx4 v[16:19], v[32:33], off offset:16
	global_load_dwordx4 v[20:23], v[50:51], off offset:16
	global_load_dwordx4 v[24:27], v[50:51], off offset:32
	global_load_dwordx4 v[28:31], v[32:33], off offset:32
	s_nop 0
	global_load_dwordx4 v[32:35], v[32:33], off offset:48
	s_nop 0
	global_load_dwordx4 v[50:53], v[50:51], off offset:48
	ds_read_b64 v[54:55], v59
	s_waitcnt vmcnt(9)
	v_lshlrev_b32_e32 v79, 16, v0
	v_and_b32_e32 v0, 0xffff0000, v0
	v_lshlrev_b32_e32 v80, 16, v1
	v_and_b32_e32 v1, 0xffff0000, v1
	v_lshlrev_b32_e32 v81, 16, v2
	v_and_b32_e32 v2, 0xffff0000, v2
	v_lshlrev_b32_e32 v82, 16, v3
	v_and_b32_e32 v3, 0xffff0000, v3
	s_waitcnt vmcnt(8)
	v_lshlrev_b32_e32 v83, 16, v4
	v_and_b32_e32 v4, 0xffff0000, v4
	v_lshlrev_b32_e32 v84, 16, v5
	s_waitcnt lgkmcnt(0)
	v_sub_f32_e32 v79, v79, v54
	v_sub_f32_e32 v0, v0, v54
	v_sub_f32_e32 v80, v80, v54
	v_sub_f32_e32 v1, v1, v54
	v_sub_f32_e32 v81, v81, v54
	v_sub_f32_e32 v2, v2, v54
	v_sub_f32_e32 v82, v82, v54
	v_sub_f32_e32 v3, v3, v54
	v_sub_f32_e32 v83, v83, v54
	v_sub_f32_e32 v4, v4, v54
	v_sub_f32_e32 v84, v84, v54
	v_mul_f32_e32 v79, v55, v79
	v_mul_f32_e32 v0, v55, v0
	v_mul_f32_e32 v80, v55, v80
	v_mul_f32_e32 v1, v55, v1
	v_mul_f32_e32 v81, v55, v81
	v_mul_f32_e32 v2, v55, v2
	v_mul_f32_e32 v82, v55, v82
	v_mul_f32_e32 v3, v55, v3
	v_mul_f32_e32 v83, v55, v83
	v_mul_f32_e32 v4, v55, v4
	v_mul_f32_e32 v84, v55, v84
	s_waitcnt vmcnt(6)
	v_fma_f32 v8, v12, v79, v8
	v_fma_f32 v0, v13, v0, v9
	v_fma_f32 v9, v80, v14, v10
	v_fmac_f32_e32 v11, v1, v15
	s_waitcnt vmcnt(4)
	v_fma_f32 v1, v81, v16, v20
	v_fma_f32 v2, v2, v17, v21
	v_fma_f32 v10, v82, v18, v22
	v_fmac_f32_e32 v23, v3, v19
	s_waitcnt vmcnt(2)
	v_fma_f32 v3, v28, v83, v24
	v_fma_f32 v4, v29, v4, v25
	v_fma_f32 v12, v84, v30, v26
	v_cvt_pk_bf16_f32 v8, v8, s0
	v_cvt_pk_bf16_f32 v0, v0, s0
	v_cvt_pk_bf16_f32 v9, v9, s0
	v_cvt_pk_bf16_f32 v11, v11, s0
	v_cvt_pk_bf16_f32 v1, v1, s0
	v_cvt_pk_bf16_f32 v2, v2, s0
	v_cvt_pk_bf16_f32 v10, v10, s0
	v_cvt_pk_bf16_f32 v13, v23, s0
	v_cvt_pk_bf16_f32 v3, v3, s0
	v_cvt_pk_bf16_f32 v4, v4, s0
	v_cvt_pk_bf16_f32 v12, v12, s0
	ds_write_b16 v61, v8 offset:1024
	ds_write_b16 v62, v0 offset:1296
	ds_write_b16 v61, v9 offset:1568
	ds_write_b16 v62, v11 offset:1840
	ds_write_b16 v61, v1 offset:2112
	ds_write_b16 v62, v2 offset:2384
	ds_write_b16 v61, v10 offset:2656
	ds_write_b16 v62, v13 offset:2928
	ds_write_b16 v61, v3 offset:3200
	ds_write_b16 v62, v4 offset:3472
	ds_write_b16 v61, v12 offset:3744
	v_and_b32_e32 v0, 0xffff0000, v5
	v_sub_f32_e32 v0, v0, v54
	v_mul_f32_e32 v0, v55, v0
	v_fmac_f32_e32 v27, v0, v31
	v_cvt_pk_bf16_f32 v0, v27, s0
	ds_write_b16 v62, v0 offset:4016
	v_lshlrev_b32_e32 v0, 16, v6
	v_sub_f32_e32 v0, v0, v54
	v_mul_f32_e32 v0, v55, v0
	s_waitcnt vmcnt(0)
	v_fma_f32 v0, v0, v32, v50
	v_cvt_pk_bf16_f32 v0, v0, s0
	ds_write_b16 v61, v0 offset:4288
	v_and_b32_e32 v0, 0xffff0000, v6
	v_sub_f32_e32 v0, v0, v54
	v_mul_f32_e32 v0, v55, v0
	v_fma_f32 v0, v0, v33, v51
	v_cvt_pk_bf16_f32 v0, v0, s0
	ds_write_b16 v62, v0 offset:4560
	v_lshlrev_b32_e32 v0, 16, v7
	v_sub_f32_e32 v0, v0, v54
	v_mul_f32_e32 v0, v55, v0
	v_fma_f32 v0, v0, v34, v52
	v_cvt_pk_bf16_f32 v0, v0, s0
	ds_write_b16 v61, v0 offset:4832
	v_and_b32_e32 v0, 0xffff0000, v7
	v_sub_f32_e32 v0, v0, v54
	v_mul_f32_e32 v0, v55, v0
	v_fmac_f32_e32 v53, v0, v35
	v_cvt_pk_bf16_f32 v0, v53, s0
	ds_write_b16 v62, v0 offset:5104
	s_waitcnt lgkmcnt(0)
	s_barrier
	s_and_saveexec_b64 s[6:7], s[4:5]
	s_cbranch_execz .LBB0_481
	s_lshl_b32 s16, s8, 15
	s_mov_b32 s17, s55
	v_lshl_add_u64 v[54:55], v[44:45], 0, s[16:17]
	global_load_dwordx4 v[104:107], v[54:55], off
	global_load_dwordx4 v[108:111], v[54:55], off offset:32
	global_load_dwordx4 v[112:115], v[54:55], off offset:64
	global_load_dwordx4 v[116:119], v[54:55], off offset:96
	global_load_dwordx4 v[120:123], v[54:55], off offset:128
	global_load_dwordx4 v[124:127], v[54:55], off offset:160
	global_load_dwordx4 v[128:131], v[54:55], off offset:192
	global_load_dwordx4 v[132:135], v[54:55], off offset:224
	ds_read_b128 v[178:181], v78 offset:1024
	ds_read_b128 v[182:185], v78 offset:9728
	s_lshl_b32 s8, s8, 6
	s_or_b32 s16, s54, s10
	s_lshl_b32 s54, s8, 1
	s_load_dwordx2 s[8:9], s[12:13], 0x98
	v_lshl_add_u64 v[50:51], v[40:41], 0, s[54:55]
	v_lshl_add_u64 v[52:53], v[42:43], 0, s[54:55]
	v_add_u32_e32 v220, s15, v60
	v_ashrrev_i32_e32 v221, 31, v220
	v_lshlrev_b64 v[222:223], 10, v[220:221]
	v_lshl_add_u64 v[222:223], v[50:51], 0, v[222:223]
	global_load_ushort v136, v[222:223], off
	global_load_ushort v152, v[222:223], off offset:64
	v_add_u32_e32 v220, s15, v63
	v_ashrrev_i32_e32 v221, 31, v220
	v_lshlrev_b64 v[224:225], 10, v[220:221]
	v_lshl_add_u64 v[224:225], v[50:51], 0, v[224:225]
	global_load_ushort v137, v[224:225], off
	global_load_ushort v153, v[224:225], off offset:64
	v_add_u32_e32 v220, s15, v64
	v_ashrrev_i32_e32 v221, 31, v220
	v_lshlrev_b64 v[222:223], 10, v[220:221]
	v_lshl_add_u64 v[222:223], v[50:51], 0, v[222:223]
	global_load_ushort v138, v[222:223], off
	global_load_ushort v154, v[222:223], off offset:64
	v_add_u32_e32 v220, s15, v65
	v_ashrrev_i32_e32 v221, 31, v220
	v_lshlrev_b64 v[224:225], 10, v[220:221]
	v_lshl_add_u64 v[224:225], v[50:51], 0, v[224:225]
	global_load_ushort v139, v[224:225], off
	global_load_ushort v155, v[224:225], off offset:64
	v_add_u32_e32 v220, s15, v66
	v_ashrrev_i32_e32 v221, 31, v220
	v_lshlrev_b64 v[222:223], 10, v[220:221]
	v_lshl_add_u64 v[222:223], v[50:51], 0, v[222:223]
	global_load_ushort v140, v[222:223], off
	global_load_ushort v156, v[222:223], off offset:64
	v_add_u32_e32 v220, s15, v67
	v_ashrrev_i32_e32 v221, 31, v220
	v_lshlrev_b64 v[224:225], 10, v[220:221]
	v_lshl_add_u64 v[224:225], v[50:51], 0, v[224:225]
	global_load_ushort v141, v[224:225], off
	global_load_ushort v157, v[224:225], off offset:64
	v_add_u32_e32 v220, s15, v68
	v_ashrrev_i32_e32 v221, 31, v220
	v_lshlrev_b64 v[222:223], 10, v[220:221]
	v_lshl_add_u64 v[222:223], v[50:51], 0, v[222:223]
	global_load_ushort v142, v[222:223], off
	global_load_ushort v158, v[222:223], off offset:64
	v_add_u32_e32 v220, s15, v69
	v_ashrrev_i32_e32 v221, 31, v220
	v_lshlrev_b64 v[224:225], 10, v[220:221]
	v_lshl_add_u64 v[224:225], v[50:51], 0, v[224:225]
	global_load_ushort v143, v[224:225], off
	global_load_ushort v159, v[224:225], off offset:64
	v_add_u32_e32 v220, s15, v70
	v_ashrrev_i32_e32 v221, 31, v220
	v_lshlrev_b64 v[222:223], 10, v[220:221]
	v_lshl_add_u64 v[222:223], v[50:51], 0, v[222:223]
	global_load_ushort v144, v[222:223], off
	global_load_ushort v160, v[222:223], off offset:64
	v_add_u32_e32 v220, s15, v71
	v_ashrrev_i32_e32 v221, 31, v220
	v_lshlrev_b64 v[224:225], 10, v[220:221]
	v_lshl_add_u64 v[224:225], v[50:51], 0, v[224:225]
	global_load_ushort v145, v[224:225], off
	global_load_ushort v161, v[224:225], off offset:64
	v_add_u32_e32 v220, s15, v72
	v_ashrrev_i32_e32 v221, 31, v220
	v_lshlrev_b64 v[222:223], 10, v[220:221]
	v_lshl_add_u64 v[222:223], v[50:51], 0, v[222:223]
	global_load_ushort v146, v[222:223], off
	global_load_ushort v162, v[222:223], off offset:64
	v_add_u32_e32 v220, s15, v73
	v_ashrrev_i32_e32 v221, 31, v220
	v_lshlrev_b64 v[224:225], 10, v[220:221]
	v_lshl_add_u64 v[224:225], v[50:51], 0, v[224:225]
	global_load_ushort v147, v[224:225], off
	global_load_ushort v163, v[224:225], off offset:64
	v_add_u32_e32 v220, s15, v74
	v_ashrrev_i32_e32 v221, 31, v220
	v_lshlrev_b64 v[222:223], 10, v[220:221]
	v_lshl_add_u64 v[222:223], v[50:51], 0, v[222:223]
	global_load_ushort v148, v[222:223], off
	global_load_ushort v164, v[222:223], off offset:64
	v_add_u32_e32 v220, s15, v75
	v_ashrrev_i32_e32 v221, 31, v220
	v_lshlrev_b64 v[224:225], 10, v[220:221]
	v_lshl_add_u64 v[224:225], v[50:51], 0, v[224:225]
	global_load_ushort v149, v[224:225], off
	global_load_ushort v165, v[224:225], off offset:64
	v_add_u32_e32 v220, s15, v76
	v_ashrrev_i32_e32 v221, 31, v220
	v_lshlrev_b64 v[222:223], 10, v[220:221]
	v_lshl_add_u64 v[222:223], v[50:51], 0, v[222:223]
	global_load_ushort v150, v[222:223], off
	global_load_ushort v172, v[222:223], off offset:64
	v_add_u32_e32 v220, s15, v77
	v_ashrrev_i32_e32 v221, 31, v220
	v_lshlrev_b64 v[224:225], 10, v[220:221]
	v_lshl_add_u64 v[224:225], v[50:51], 0, v[224:225]
	global_load_ushort v151, v[224:225], off
	global_load_ushort v173, v[224:225], off offset:64
	v_add_u32_e32 v220, s16, v60
	v_ashrrev_i32_e32 v221, 31, v220
	s_waitcnt lgkmcnt(0)
	v_lshl_add_u64 v[230:231], v[220:221], 2, s[8:9]
	global_load_dwordx4 v[204:207], v[230:231], off
	global_load_dwordx4 v[208:211], v[230:231], off offset:32
	global_load_dwordx4 v[212:215], v[230:231], off offset:64
	global_load_dwordx4 v[216:219], v[230:231], off offset:96
	s_waitcnt vmcnt(36)
	ds_read_b128 v[186:189], v78 offset:1056
	ds_read_b128 v[192:195], v78 offset:9760
	s_waitcnt lgkmcnt(2)
	v_mfma_f32_32x32x16_bf16 v[0:15], v[104:107], v[178:181], 0
	v_mfma_f32_32x32x16_bf16 v[16:31], v[104:107], v[182:185], 0
	ds_read_b128 v[178:181], v78 offset:1088
	ds_read_b128 v[182:185], v78 offset:9792
	s_waitcnt lgkmcnt(2)
	v_mfma_f32_32x32x16_bf16 v[0:15], v[108:111], v[186:189], v[0:15]
	v_mfma_f32_32x32x16_bf16 v[16:31], v[108:111], v[192:195], v[16:31]
	ds_read_b128 v[186:189], v78 offset:1120
	ds_read_b128 v[192:195], v78 offset:9824
	s_waitcnt lgkmcnt(2)
	v_mfma_f32_32x32x16_bf16 v[0:15], v[112:115], v[178:181], v[0:15]
	v_mfma_f32_32x32x16_bf16 v[16:31], v[112:115], v[182:185], v[16:31]
	ds_read_b128 v[178:181], v78 offset:1152
	ds_read_b128 v[182:185], v78 offset:9856
	s_waitcnt lgkmcnt(2)
	v_mfma_f32_32x32x16_bf16 v[0:15], v[116:119], v[186:189], v[0:15]
	v_mfma_f32_32x32x16_bf16 v[16:31], v[116:119], v[192:195], v[16:31]
	ds_read_b128 v[186:189], v78 offset:1184
	ds_read_b128 v[192:195], v78 offset:9888
	s_waitcnt lgkmcnt(2)
	v_mfma_f32_32x32x16_bf16 v[0:15], v[120:123], v[178:181], v[0:15]
	v_mfma_f32_32x32x16_bf16 v[16:31], v[120:123], v[182:185], v[16:31]
	ds_read_b128 v[178:181], v78 offset:1216
	ds_read_b128 v[182:185], v78 offset:9920
	s_waitcnt lgkmcnt(2)
	v_mfma_f32_32x32x16_bf16 v[0:15], v[124:127], v[186:189], v[0:15]
	v_mfma_f32_32x32x16_bf16 v[16:31], v[124:127], v[192:195], v[16:31]
	ds_read_b128 v[186:189], v78 offset:1248
	ds_read_b128 v[192:195], v78 offset:9952
	s_waitcnt lgkmcnt(2)
	v_mfma_f32_32x32x16_bf16 v[0:15], v[128:131], v[178:181], v[0:15]
	v_mfma_f32_32x32x16_bf16 v[16:31], v[128:131], v[182:185], v[16:31]
	s_waitcnt lgkmcnt(0)
	v_mfma_f32_32x32x16_bf16 v[0:15], v[132:135], v[186:189], v[0:15]
	v_mfma_f32_32x32x16_bf16 v[16:31], v[132:135], v[192:195], v[16:31]
	s_waitcnt vmcnt(0)
	s_nop 7
	s_nop 3
	v_add_u32_e32 v220, s15, v60
	v_mad_i64_i32 v[222:223], s[22:23], v220, s78, v[52:53]
	v_lshlrev_b32_e32 v136, 16, v136
	v_lshlrev_b32_e32 v152, 16, v152
	v_add_f32_e32 v226, v0, v204
	v_add_f32_e32 v227, v16, v204
	v_mul_f32_e32 v226, v226, v136
	v_mul_f32_e32 v227, v227, v152
	v_cvt_pk_bf16_f32 v226, v226, s0
	v_cvt_pk_bf16_f32 v227, v227, s0
	global_store_short v[222:223], v226, off
	global_store_short v[222:223], v227, off offset:64
	v_add_u32_e32 v220, s15, v63
	v_mad_i64_i32 v[224:225], s[22:23], v220, s78, v[52:53]
	v_lshlrev_b32_e32 v137, 16, v137
	v_lshlrev_b32_e32 v153, 16, v153
	v_add_f32_e32 v228, v1, v205
	v_add_f32_e32 v229, v17, v205
	v_mul_f32_e32 v228, v228, v137
	v_mul_f32_e32 v229, v229, v153
	v_cvt_pk_bf16_f32 v228, v228, s0
	v_cvt_pk_bf16_f32 v229, v229, s0
	global_store_short v[224:225], v228, off
	global_store_short v[224:225], v229, off offset:64
	v_add_u32_e32 v220, s15, v64
	v_mad_i64_i32 v[222:223], s[22:23], v220, s78, v[52:53]
	v_lshlrev_b32_e32 v138, 16, v138
	v_lshlrev_b32_e32 v154, 16, v154
	v_add_f32_e32 v226, v2, v206
	v_add_f32_e32 v227, v18, v206
	v_mul_f32_e32 v226, v226, v138
	v_mul_f32_e32 v227, v227, v154
	v_cvt_pk_bf16_f32 v226, v226, s0
	v_cvt_pk_bf16_f32 v227, v227, s0
	global_store_short v[222:223], v226, off
	global_store_short v[222:223], v227, off offset:64
	v_add_u32_e32 v220, s15, v65
	v_mad_i64_i32 v[224:225], s[22:23], v220, s78, v[52:53]
	v_lshlrev_b32_e32 v139, 16, v139
	v_lshlrev_b32_e32 v155, 16, v155
	v_add_f32_e32 v228, v3, v207
	v_add_f32_e32 v229, v19, v207
	v_mul_f32_e32 v228, v228, v139
	v_mul_f32_e32 v229, v229, v155
	v_cvt_pk_bf16_f32 v228, v228, s0
	v_cvt_pk_bf16_f32 v229, v229, s0
	global_store_short v[224:225], v228, off
	global_store_short v[224:225], v229, off offset:64
	v_add_u32_e32 v220, s15, v66
	v_mad_i64_i32 v[222:223], s[22:23], v220, s78, v[52:53]
	v_lshlrev_b32_e32 v140, 16, v140
	v_lshlrev_b32_e32 v156, 16, v156
	v_add_f32_e32 v226, v4, v208
	v_add_f32_e32 v227, v20, v208
	v_mul_f32_e32 v226, v226, v140
	v_mul_f32_e32 v227, v227, v156
	v_cvt_pk_bf16_f32 v226, v226, s0
	v_cvt_pk_bf16_f32 v227, v227, s0
	global_store_short v[222:223], v226, off
	global_store_short v[222:223], v227, off offset:64
	v_add_u32_e32 v220, s15, v67
	v_mad_i64_i32 v[224:225], s[22:23], v220, s78, v[52:53]
	v_lshlrev_b32_e32 v141, 16, v141
	v_lshlrev_b32_e32 v157, 16, v157
	v_add_f32_e32 v228, v5, v209
	v_add_f32_e32 v229, v21, v209
	v_mul_f32_e32 v228, v228, v141
	v_mul_f32_e32 v229, v229, v157
	v_cvt_pk_bf16_f32 v228, v228, s0
	v_cvt_pk_bf16_f32 v229, v229, s0
	global_store_short v[224:225], v228, off
	global_store_short v[224:225], v229, off offset:64
	v_add_u32_e32 v220, s15, v68
	v_mad_i64_i32 v[222:223], s[22:23], v220, s78, v[52:53]
	v_lshlrev_b32_e32 v142, 16, v142
	v_lshlrev_b32_e32 v158, 16, v158
	v_add_f32_e32 v226, v6, v210
	v_add_f32_e32 v227, v22, v210
	v_mul_f32_e32 v226, v226, v142
	v_mul_f32_e32 v227, v227, v158
	v_cvt_pk_bf16_f32 v226, v226, s0
	v_cvt_pk_bf16_f32 v227, v227, s0
	global_store_short v[222:223], v226, off
	global_store_short v[222:223], v227, off offset:64
	v_add_u32_e32 v220, s15, v69
	v_mad_i64_i32 v[224:225], s[22:23], v220, s78, v[52:53]
	v_lshlrev_b32_e32 v143, 16, v143
	v_lshlrev_b32_e32 v159, 16, v159
	v_add_f32_e32 v228, v7, v211
	v_add_f32_e32 v229, v23, v211
	v_mul_f32_e32 v228, v228, v143
	v_mul_f32_e32 v229, v229, v159
	v_cvt_pk_bf16_f32 v228, v228, s0
	v_cvt_pk_bf16_f32 v229, v229, s0
	global_store_short v[224:225], v228, off
	global_store_short v[224:225], v229, off offset:64
	v_add_u32_e32 v220, s15, v70
	v_mad_i64_i32 v[222:223], s[22:23], v220, s78, v[52:53]
	v_lshlrev_b32_e32 v144, 16, v144
	v_lshlrev_b32_e32 v160, 16, v160
	v_add_f32_e32 v226, v8, v212
	v_add_f32_e32 v227, v24, v212
	v_mul_f32_e32 v226, v226, v144
	v_mul_f32_e32 v227, v227, v160
	v_cvt_pk_bf16_f32 v226, v226, s0
	v_cvt_pk_bf16_f32 v227, v227, s0
	global_store_short v[222:223], v226, off
	global_store_short v[222:223], v227, off offset:64
	v_add_u32_e32 v220, s15, v71
	v_mad_i64_i32 v[224:225], s[22:23], v220, s78, v[52:53]
	v_lshlrev_b32_e32 v145, 16, v145
	v_lshlrev_b32_e32 v161, 16, v161
	v_add_f32_e32 v228, v9, v213
	v_add_f32_e32 v229, v25, v213
	v_mul_f32_e32 v228, v228, v145
	v_mul_f32_e32 v229, v229, v161
	v_cvt_pk_bf16_f32 v228, v228, s0
	v_cvt_pk_bf16_f32 v229, v229, s0
	global_store_short v[224:225], v228, off
	global_store_short v[224:225], v229, off offset:64
	v_add_u32_e32 v220, s15, v72
	v_mad_i64_i32 v[222:223], s[22:23], v220, s78, v[52:53]
	v_lshlrev_b32_e32 v146, 16, v146
	v_lshlrev_b32_e32 v162, 16, v162
	v_add_f32_e32 v226, v10, v214
	v_add_f32_e32 v227, v26, v214
	v_mul_f32_e32 v226, v226, v146
	v_mul_f32_e32 v227, v227, v162
	v_cvt_pk_bf16_f32 v226, v226, s0
	v_cvt_pk_bf16_f32 v227, v227, s0
	global_store_short v[222:223], v226, off
	global_store_short v[222:223], v227, off offset:64
	v_add_u32_e32 v220, s15, v73
	v_mad_i64_i32 v[224:225], s[22:23], v220, s78, v[52:53]
	v_lshlrev_b32_e32 v147, 16, v147
	v_lshlrev_b32_e32 v163, 16, v163
	v_add_f32_e32 v228, v11, v215
	v_add_f32_e32 v229, v27, v215
	v_mul_f32_e32 v228, v228, v147
	v_mul_f32_e32 v229, v229, v163
	v_cvt_pk_bf16_f32 v228, v228, s0
	v_cvt_pk_bf16_f32 v229, v229, s0
	global_store_short v[224:225], v228, off
	global_store_short v[224:225], v229, off offset:64
	v_add_u32_e32 v220, s15, v74
	v_mad_i64_i32 v[222:223], s[22:23], v220, s78, v[52:53]
	v_lshlrev_b32_e32 v148, 16, v148
	v_lshlrev_b32_e32 v164, 16, v164
	v_add_f32_e32 v226, v12, v216
	v_add_f32_e32 v227, v28, v216
	v_mul_f32_e32 v226, v226, v148
	v_mul_f32_e32 v227, v227, v164
	v_cvt_pk_bf16_f32 v226, v226, s0
	v_cvt_pk_bf16_f32 v227, v227, s0
	global_store_short v[222:223], v226, off
	global_store_short v[222:223], v227, off offset:64
	v_add_u32_e32 v220, s15, v75
	v_mad_i64_i32 v[224:225], s[22:23], v220, s78, v[52:53]
	v_lshlrev_b32_e32 v149, 16, v149
	v_lshlrev_b32_e32 v165, 16, v165
	v_add_f32_e32 v228, v13, v217
	v_add_f32_e32 v229, v29, v217
	v_mul_f32_e32 v228, v228, v149
	v_mul_f32_e32 v229, v229, v165
	v_cvt_pk_bf16_f32 v228, v228, s0
	v_cvt_pk_bf16_f32 v229, v229, s0
	global_store_short v[224:225], v228, off
	global_store_short v[224:225], v229, off offset:64
	v_add_u32_e32 v220, s15, v76
	v_mad_i64_i32 v[222:223], s[22:23], v220, s78, v[52:53]
	v_lshlrev_b32_e32 v150, 16, v150
	v_lshlrev_b32_e32 v172, 16, v172
	v_add_f32_e32 v226, v14, v218
	v_add_f32_e32 v227, v30, v218
	v_mul_f32_e32 v226, v226, v150
	v_mul_f32_e32 v227, v227, v172
	v_cvt_pk_bf16_f32 v226, v226, s0
	v_cvt_pk_bf16_f32 v227, v227, s0
	global_store_short v[222:223], v226, off
	global_store_short v[222:223], v227, off offset:64
	v_add_u32_e32 v220, s15, v77
	v_mad_i64_i32 v[224:225], s[22:23], v220, s78, v[52:53]
	v_lshlrev_b32_e32 v151, 16, v151
	v_lshlrev_b32_e32 v173, 16, v173
	v_add_f32_e32 v228, v15, v219
	v_add_f32_e32 v229, v31, v219
	v_mul_f32_e32 v228, v228, v151
	v_mul_f32_e32 v229, v229, v173
	v_cvt_pk_bf16_f32 v228, v228, s0
	v_cvt_pk_bf16_f32 v229, v229, s0
	global_store_short v[224:225], v228, off
	global_store_short v[224:225], v229, off offset:64
	s_branch .LBB0_481
